# v11 + prompt attention: Q0 fragment read hoisted above the step barrier, step-head wait lgkmcnt(0)->lgkmcnt(2)
# speedup vs baseline: 1.0053x; 1.0053x over previous
.LBB0_1066:
	s_and_b32 s0, s66, 0x3fffffc0
	s_lshl_b32 s0, s0, 2
	s_add_i32 s85, s0, 0
	s_add_i32 s5, s5, 3
	s_add_i32 s85, s85, 0x18000
	s_and_b32 s0, s5, -2
	s_cmp_gt_i32 s4, 1
	s_cselect_b32 s86, s0, 4
	s_lshl_b32 s0, s67, 13
	s_add_i32 s0, s0, 0
	v_lshlrev_b32_e32 v2, 10, v236
	v_lshlrev_b32_e32 v20, 4, v235
	v_add3_u32 v247, s0, v2, v20
	s_waitcnt vmcnt(6) lgkmcnt(0)
	s_barrier
	ds_read_b128 v[54:57], v247
	ds_read_b128 v[58:61], v247 offset:512
	s_waitcnt lgkmcnt(1)
	v_mfma_f32_32x32x16_bf16 v[20:35], v[54:57], v[48:51], v[4:19]
	v_lshlrev_b32_e32 v2, 1, v52
	v_and_b32_e32 v241, 32, v2
	v_lshlrev_b32_e32 v2, 4, v52
	v_and_b32_e32 v2, 0xc0, v2
	v_lshl_or_b32 v240, v236, 8, v2
	v_add_u32_e32 v2, 0, v241
	v_add3_u32 v246, v2, v239, v240
	s_waitcnt lgkmcnt(0)
	v_mfma_f32_32x32x16_bf16 v[4:19], v[58:61], v[48:51], v[4:19]
	ds_read_b128 v[48:51], v247 offset:2048
	ds_read_b128 v[54:57], v247 offset:2560
	s_min_i32 s0, s91, 3
	s_ashr_i32 s1, s0, 31
	s_lshl_b64 s[0:1], s[0:1], 17
	s_add_u32 s0, s87, s0
	s_addc_u32 s1, s88, s1
	s_mov_b32 s93, 1
	s_waitcnt lgkmcnt(1)
	v_mfma_f32_32x32x16_bf16 v[20:35], v[48:51], v[44:47], v[20:35]
	s_mov_b32 s34, 0
	v_lshl_add_u32 v242, v235, 2, s85
	s_waitcnt lgkmcnt(0)
	v_mfma_f32_32x32x16_bf16 v[4:19], v[54:57], v[44:47], v[4:19]
	ds_read_b128 v[44:47], v247 offset:4096
	ds_read_b128 v[48:51], v247 offset:4608
	s_waitcnt lgkmcnt(1)
	v_mfma_f32_32x32x16_bf16 v[20:35], v[44:47], v[40:43], v[20:35]
	s_waitcnt lgkmcnt(0)
	v_mfma_f32_32x32x16_bf16 v[4:19], v[48:51], v[40:43], v[4:19]
	ds_read_b128 v[40:43], v247 offset:6144
	ds_read_b128 v[44:47], v247 offset:6656
	s_waitcnt lgkmcnt(1)
	v_mfma_f32_32x32x16_bf16 v[20:35], v[40:43], v[36:39], v[20:35]
	s_waitcnt lgkmcnt(0)
	v_mfma_f32_32x32x16_bf16 v[4:19], v[44:47], v[36:39], v[4:19]
	s_nop 15
	s_nop 7
	s_nop 0
	v_max3_f32 v2, v20, v21, v4
	v_max3_f32 v36, v22, v23, v5
	s_nop 0
	v_max3_f32 v2, v2, v6, v7
	v_max3_f32 v36, v36, v26, v27
	s_nop 0
	v_max3_f32 v2, v2, v24, v25
	v_max3_f32 v36, v36, v10, v11
	s_nop 0
	v_max3_f32 v2, v2, v8, v9
	v_max3_f32 v36, v36, v30, v31
	s_nop 0
	v_max3_f32 v2, v2, v28, v29
	v_max3_f32 v36, v36, v14, v15
	s_nop 0
	v_max3_f32 v2, v2, v12, v13
	v_max3_f32 v36, v36, v34, v35
	s_nop 0
	v_max3_f32 v2, v2, v32, v33
	v_max3_f32 v36, v36, v18, v19
	s_nop 0
	v_max3_f32 v2, v2, v16, v17
	s_nop 0
	v_max_f32_e32 v2, v2, v36
	s_nop 0
	v_mov_b32_e32 v36, v2
	s_nop 1
	v_permlane32_swap_b32_e32 v2, v36
	v_max_f32_e32 v2, v2, v36
	s_nop 0
	v_add_f32_e32 v245, v3, v2
	v_sub_f32_e32 v20, v20, v2
	v_sub_f32_e32 v4, v4, v2
	v_sub_f32_e32 v21, v21, v2
	v_sub_f32_e32 v5, v5, v2
	v_sub_f32_e32 v22, v22, v2
	s_nop 0
	v_xor_b32_e32 v82, 0x80000000, v245
	v_mov_b32_e32 v83, v82
	v_mov_b32_e32 v84, v82
	v_mov_b32_e32 v85, v82
	v_mov_b32_e32 v86, v82
	v_mov_b32_e32 v87, v82
	v_mov_b32_e32 v88, v82
	v_mov_b32_e32 v89, v82
	v_mov_b32_e32 v90, v82
	v_mov_b32_e32 v91, v82
	v_mov_b32_e32 v92, v82
	v_mov_b32_e32 v93, v82
	v_mov_b32_e32 v94, v82
	v_mov_b32_e32 v95, v82
	v_mov_b32_e32 v96, v82
	v_mov_b32_e32 v97, v82
	s_waitcnt vmcnt(0) lgkmcnt(0)
	s_barrier
	s_mov_b32 s2, m0
	s_mov_b32 m0, s81
	s_nop 4
	global_load_lds_dwordx4 v237, s[0:1]
	s_mov_b32 m0, s2
	s_add_u32 s0, s0, 0x80
	s_addc_u32 s1, s1, 0
	s_cmp_lg_u32 0, -1
	s_cselect_b32 s2, 0, 0
	s_add_i32 s2, s2, s79
	s_add_i32 s82, s2, 0x2000
	s_mov_b32 s3, m0
	s_mov_b32 m0, s82
	s_nop 4
	global_load_lds_dwordx4 v237, s[0:1]
	s_mov_b32 m0, s3
	s_min_i32 s0, s91, 1
	s_ashr_i32 s1, s0, 31
	s_lshl_b64 s[0:1], s[0:1], 17
	s_add_u32 s0, s89, s0
	s_addc_u32 s1, s90, s1
	s_add_i32 s3, s2, 0x10000
	s_mov_b32 s4, m0
	s_mov_b32 m0, s3
	s_nop 4
	global_load_lds_dwordx4 v238, s[0:1]
	s_mov_b32 m0, s4
	s_add_u32 s0, s0, 0x80
	s_addc_u32 s1, s1, 0
	s_add_i32 s84, s2, 0xe000
	s_add_i32 s2, s2, 0x12000
	s_mov_b32 s3, m0
	s_mov_b32 m0, s2
	s_nop 4
	global_load_lds_dwordx4 v238, s[0:1]
	s_mov_b32 m0, s3
	ds_read_b128 v[206:209], v247 offset:16384
	ds_read_b128 v[202:205], v247 offset:16896
	ds_read_b128 v[198:201], v247 offset:18432
	ds_read_b128 v[194:197], v247 offset:18944
	ds_read_b128 v[190:193], v247 offset:20480
	ds_read_b128 v[186:189], v247 offset:20992
	ds_read_b128 v[182:185], v247 offset:22528
	ds_read_b128 v[178:181], v247 offset:23040
	v_sub_f32_e32 v6, v6, v2
	v_sub_f32_e32 v23, v23, v2
	v_sub_f32_e32 v7, v7, v2
	v_sub_f32_e32 v24, v24, v2
	v_sub_f32_e32 v8, v8, v2
	v_sub_f32_e32 v25, v25, v2
	v_sub_f32_e32 v9, v9, v2
	v_sub_f32_e32 v26, v26, v2
	v_sub_f32_e32 v10, v10, v2
	v_sub_f32_e32 v27, v27, v2
	v_sub_f32_e32 v11, v11, v2
	v_sub_f32_e32 v28, v28, v2
	v_sub_f32_e32 v12, v12, v2
	v_sub_f32_e32 v29, v29, v2
	v_sub_f32_e32 v13, v13, v2
	v_sub_f32_e32 v30, v30, v2
	v_sub_f32_e32 v14, v14, v2
	v_sub_f32_e32 v31, v31, v2
	v_sub_f32_e32 v15, v15, v2
	v_sub_f32_e32 v32, v32, v2
	v_sub_f32_e32 v16, v16, v2
	v_sub_f32_e32 v33, v33, v2
	v_sub_f32_e32 v17, v17, v2
	v_sub_f32_e32 v34, v34, v2
	v_sub_f32_e32 v18, v18, v2
	v_sub_f32_e32 v35, v35, v2
	v_sub_f32_e32 v2, v19, v2
	v_exp_f32_e32 v114, v20
	v_exp_f32_e32 v115, v21
	v_exp_f32_e32 v116, v22
	v_exp_f32_e32 v117, v23
	v_exp_f32_e32 v118, v24
	v_exp_f32_e32 v119, v25
	v_exp_f32_e32 v120, v26
	v_exp_f32_e32 v121, v27
	v_exp_f32_e32 v122, v28
	v_exp_f32_e32 v123, v29
	v_exp_f32_e32 v124, v30
	v_exp_f32_e32 v125, v31
	v_exp_f32_e32 v126, v32
	v_exp_f32_e32 v127, v33
	v_exp_f32_e32 v128, v34
	v_exp_f32_e32 v129, v35
	v_exp_f32_e32 v98, v4
	v_exp_f32_e32 v99, v5
	v_exp_f32_e32 v100, v6
	v_exp_f32_e32 v101, v7
	v_exp_f32_e32 v102, v8
	v_exp_f32_e32 v103, v9
	v_exp_f32_e32 v104, v10
	v_exp_f32_e32 v105, v11
	v_exp_f32_e32 v106, v12
	v_exp_f32_e32 v107, v13
	v_exp_f32_e32 v108, v14
	v_exp_f32_e32 v109, v15
	v_exp_f32_e32 v110, v16
	v_exp_f32_e32 v111, v17
	v_exp_f32_e32 v112, v18
	v_exp_f32_e32 v113, v2
	s_waitcnt vmcnt(4) lgkmcnt(0)
	s_barrier
	s_cmp_lt_i32 s86, 7
	v_cmp_gt_u32_e64 s[2:3], 32, v233
	s_cbranch_scc1 .LBB0_1083
	v_mov_b32_e32 v16, v3
	v_mov_b32_e32 v17, v3
	v_mov_b32_e32 v2, v3
	v_mov_b32_e32 v4, v3
	v_mov_b32_e32 v5, v3
	v_mov_b32_e32 v6, v3
	v_mov_b32_e32 v7, v3
	v_mov_b32_e32 v8, v3
	v_mov_b32_e32 v9, v3
	v_mov_b32_e32 v10, v3
	v_mov_b32_e32 v11, v3
	v_mov_b32_e32 v12, v3
	v_mov_b32_e32 v13, v3
	v_mov_b32_e32 v14, v3
	v_mov_b32_e32 v15, v3
	v_mov_b64_e32 v[80:81], v[16:17]
	v_mov_b64_e32 v[64:65], v[16:17]
	v_mov_b64_e32 v[48:49], v[16:17]
	v_mov_b64_e32 v[32:33], v[16:17]
	s_mov_b32 s0, 0
	s_mov_b32 s34, 0x8000
	s_movk_i32 s36, 0x4000
	v_mov_b32_e32 v248, 0
	s_mov_b32 s35, 6
	v_mov_b64_e32 v[78:79], v[14:15]
	v_mov_b64_e32 v[76:77], v[12:13]
	v_mov_b64_e32 v[74:75], v[10:11]
	v_mov_b64_e32 v[72:73], v[8:9]
	v_mov_b64_e32 v[70:71], v[6:7]
	v_mov_b64_e32 v[68:69], v[4:5]
	v_mov_b64_e32 v[66:67], v[2:3]
	v_mov_b64_e32 v[62:63], v[14:15]
	v_mov_b64_e32 v[60:61], v[12:13]
	v_mov_b64_e32 v[58:59], v[10:11]
	v_mov_b64_e32 v[56:57], v[8:9]
	v_mov_b64_e32 v[54:55], v[6:7]
	v_mov_b64_e32 v[52:53], v[4:5]
	v_mov_b64_e32 v[50:51], v[2:3]
	v_mov_b64_e32 v[46:47], v[14:15]
	v_mov_b64_e32 v[44:45], v[12:13]
	v_mov_b64_e32 v[42:43], v[10:11]
	v_mov_b64_e32 v[40:41], v[8:9]
	v_mov_b64_e32 v[38:39], v[6:7]
	v_mov_b64_e32 v[36:37], v[4:5]
	v_mov_b64_e32 v[34:35], v[2:3]
	v_mov_b64_e32 v[30:31], v[14:15]
	v_mov_b64_e32 v[28:29], v[12:13]
	v_mov_b64_e32 v[26:27], v[10:11]
	v_mov_b64_e32 v[24:25], v[8:9]
	v_mov_b64_e32 v[22:23], v[6:7]
	v_mov_b64_e32 v[20:21], v[4:5]
	v_mov_b64_e32 v[18:19], v[2:3]
	ds_read_b128 v[210:213], v244
.LBB0_1068:
	v_add_u32_e32 v16, s0, v246
	ds_read_b64_tr_b16 v[6:7], v16 offset:49664
	ds_read_b64_tr_b16 v[4:5], v16 offset:49152
	s_waitcnt lgkmcnt(2)
	v_mfma_f32_32x32x16_bf16 v[146:161], v[206:209], v[210:213], v[82:97]
	v_add_f32_e32 v2, v114, v115
	v_add_f32_e32 v2, v116, v2
	v_add_f32_e32 v2, v117, v2
	v_add_f32_e32 v2, v118, v2
	v_add_f32_e32 v2, v119, v2
	v_cvt_pk_bf16_f32 v174, v114, v115
	v_cvt_pk_bf16_f32 v175, v116, v117
	ds_read_b64_tr_b16 v[10:11], v16 offset:53760
	ds_read_b64_tr_b16 v[8:9], v16 offset:53248
	ds_read_b128 v[206:209], v244 offset:1024
	v_mfma_f32_32x32x16_bf16 v[130:145], v[202:205], v[210:213], v[82:97]
	v_add_f32_e32 v2, v120, v2
	v_add_f32_e32 v2, v121, v2
	v_add_f32_e32 v2, v122, v2
	v_add_f32_e32 v2, v123, v2
	v_cvt_pk_bf16_f32 v176, v118, v119
	v_cvt_pk_bf16_f32 v177, v120, v121
	ds_read_b64_tr_b16 v[12:13], v16 offset:50176
	ds_read_b64_tr_b16 v[14:15], v16 offset:50688
	s_waitcnt lgkmcnt(2)
	v_mfma_f32_32x32x16_bf16 v[146:161], v[198:201], v[206:209], v[146:161]
	v_add_f32_e32 v2, v124, v2
	v_add_f32_e32 v2, v125, v2
	v_add_f32_e32 v2, v126, v2
	v_add_f32_e32 v2, v127, v2
	v_cvt_pk_bf16_f32 v170, v122, v123
	v_cvt_pk_bf16_f32 v171, v124, v125
	ds_read_b64_tr_b16 v[116:117], v16 offset:54784
	ds_read_b64_tr_b16 v[114:115], v16 offset:54272
	ds_read_b128 v[122:125], v244 offset:2048
	v_mfma_f32_32x32x16_bf16 v[130:145], v[194:197], v[206:209], v[130:145]
	v_add_f32_e32 v2, v128, v2
	v_add_f32_e32 v2, v129, v2
	v_add_f32_e32 v2, v98, v2
	v_add_f32_e32 v2, v99, v2
	v_cvt_pk_bf16_f32 v172, v126, v127
	v_cvt_pk_bf16_f32 v173, v128, v129
	ds_read_b64_tr_b16 v[118:119], v16 offset:51200
	ds_read_b64_tr_b16 v[120:121], v16 offset:51712
	s_waitcnt lgkmcnt(2)
	v_mfma_f32_32x32x16_bf16 v[146:161], v[190:193], v[122:125], v[146:161]
	v_add_f32_e32 v2, v100, v2
	v_add_f32_e32 v2, v101, v2
	v_add_f32_e32 v2, v102, v2
	v_add_f32_e32 v2, v103, v2
	v_cvt_pk_bf16_f32 v166, v98, v99
	v_cvt_pk_bf16_f32 v167, v100, v101
	ds_read_b64_tr_b16 v[100:101], v16 offset:55808
	ds_read_b64_tr_b16 v[98:99], v16 offset:55296
	ds_read_b128 v[126:129], v244 offset:3072
	v_mfma_f32_32x32x16_bf16 v[130:145], v[186:189], v[122:125], v[130:145]
	v_add_f32_e32 v2, v104, v2
	v_add_f32_e32 v2, v105, v2
	v_add_f32_e32 v2, v106, v2
	v_add_f32_e32 v2, v107, v2
	v_cvt_pk_bf16_f32 v168, v102, v103
	v_cvt_pk_bf16_f32 v169, v104, v105
	ds_read_b64_tr_b16 v[102:103], v16 offset:52224
	ds_read_b64_tr_b16 v[104:105], v16 offset:52736
	s_waitcnt lgkmcnt(2)
	v_mfma_f32_32x32x16_bf16 v[146:161], v[182:185], v[126:129], v[146:161]
	v_add_f32_e32 v2, v108, v2
	v_add_f32_e32 v2, v109, v2
	v_add_f32_e32 v2, v110, v2
	v_add_f32_e32 v2, v111, v2
	v_cvt_pk_bf16_f32 v162, v106, v107
	v_cvt_pk_bf16_f32 v163, v108, v109
	ds_read_b64_tr_b16 v[106:107], v16 offset:56320
	ds_read_b64_tr_b16 v[108:109], v16 offset:56832
	v_mfma_f32_32x32x16_bf16 v[130:145], v[178:181], v[126:129], v[130:145]
	v_add_f32_e32 v2, v112, v2
	v_add_f32_e32 v2, v113, v2
	v_add_f32_e32 v2, 0, v2
	v_cvt_pk_bf16_f32 v164, v110, v111
	v_cvt_pk_bf16_f32 v165, v112, v113
	s_add_i32 s0, s35, -2
	v_max_f32_e32 v17, v147, v147
	v_max_f32_e32 v110, v146, v146
	s_min_i32 s0, s0, s91
	v_max_f32_e32 v17, v110, v17
	s_ashr_i32 s1, s0, 31
	s_nop 0
	v_max3_f32 v110, v148, v149, v131
	v_max3_f32 v17, v17, v130, v132
	s_lshl_b64 s[0:1], s[0:1], 17
	v_max3_f32 v17, v17, v133, v150
	v_max3_f32 v110, v110, v152, v153
	s_add_u32 s0, s87, s0
	v_max3_f32 v17, v17, v151, v134
	v_max3_f32 v110, v110, v136, v137
	s_addc_u32 s1, s88, s1
	s_add_i32 s4, s36, s81
	v_max3_f32 v17, v17, v135, v154
	v_max3_f32 v110, v110, v156, v157
	s_mov_b32 s5, m0
	s_mov_b32 m0, s4
	s_nop 4
	global_load_lds_dwordx4 v237, s[0:1]
	s_mov_b32 m0, s5
	s_add_u32 s0, s0, 0x80
	v_max3_f32 v17, v17, v155, v138
	v_max3_f32 v110, v110, v140, v141
	s_addc_u32 s1, s1, 0
	s_add_i32 s4, s36, s82
	s_mov_b32 s5, m0
	s_mov_b32 m0, s4
	s_nop 4
	global_load_lds_dwordx4 v237, s[0:1]
	s_mov_b32 m0, s5
	s_add_i32 s0, s35, -4
	v_max3_f32 v17, v17, v139, v158
	v_max3_f32 v110, v110, v160, v161
	s_min_i32 s0, s0, s91
	v_max3_f32 v17, v17, v159, v142
	v_max3_f32 v110, v110, v144, v145
	s_ashr_i32 s1, s0, 31
	v_max3_f32 v17, v17, v143, v110
	s_lshl_b64 s[0:1], s[0:1], 17
	v_mov_b32_e32 v110, v17
	s_add_u32 s0, s89, s0
	s_nop 0
	v_permlane32_swap_b32_e32 v17, v110
	s_addc_u32 s1, s90, s1
	s_add_i32 s4, s34, s80
	v_max_f32_e32 v110, v110, v110
	v_max_f32_e32 v17, v17, v17
	s_mov_b32 s5, m0
	s_mov_b32 m0, s4
	s_nop 4
	global_load_lds_dwordx4 v238, s[0:1]
	s_mov_b32 m0, s5
	s_add_u32 s0, s0, 0x80
	v_max_f32_e32 v17, v17, v110
	s_addc_u32 s1, s1, 0
	s_add_i32 s4, s34, s84
	s_mov_b32 s5, m0
	s_mov_b32 m0, s4
	s_nop 4
	global_load_lds_dwordx4 v238, s[0:1]
	s_mov_b32 m0, s5
	v_cmp_lt_f32_e32 vcc, s62, v17
	s_cmp_lg_u64 vcc, 0
	v_add_f32_e32 v2, v248, v2
	s_cselect_b64 s[0:1], -1, 0
	s_cbranch_vccnz .LBB0_1076
.LBB0_1069:
	v_mfma_f32_32x32x16_bf16 v[66:81], v[174:177], v[4:7], v[66:81]
	v_exp_f32_e32 v146, v146
	v_exp_f32_e32 v147, v147
	ds_read_b64_tr_b16 v[4:5], v16 offset:57344
	ds_read_b64_tr_b16 v[6:7], v16 offset:57856
	v_mfma_f32_32x32x16_bf16 v[50:65], v[174:177], v[8:11], v[50:65]
	v_exp_f32_e32 v148, v148
	v_exp_f32_e32 v149, v149
	ds_read_b64_tr_b16 v[8:9], v16 offset:61440
	ds_read_b64_tr_b16 v[10:11], v16 offset:61952
	v_mfma_f32_32x32x16_bf16 v[66:81], v[170:173], v[12:15], v[66:81]
	v_exp_f32_e32 v150, v150
	v_exp_f32_e32 v151, v151
	ds_read_b64_tr_b16 v[12:13], v16 offset:58368
	ds_read_b64_tr_b16 v[14:15], v16 offset:58880
	v_mfma_f32_32x32x16_bf16 v[50:65], v[170:173], v[114:117], v[50:65]
	v_exp_f32_e32 v152, v152
	v_exp_f32_e32 v153, v153
	ds_read_b64_tr_b16 v[110:111], v16 offset:62464
	ds_read_b64_tr_b16 v[112:113], v16 offset:62976
	v_mfma_f32_32x32x16_bf16 v[66:81], v[166:169], v[118:121], v[66:81]
	v_exp_f32_e32 v154, v154
	v_exp_f32_e32 v155, v155
	ds_read_b64_tr_b16 v[114:115], v16 offset:59392
	ds_read_b64_tr_b16 v[116:117], v16 offset:59904
	v_mfma_f32_32x32x16_bf16 v[50:65], v[166:169], v[98:101], v[50:65]
	v_exp_f32_e32 v156, v156
	v_exp_f32_e32 v157, v157
	ds_read_b64_tr_b16 v[118:119], v16 offset:63488
	ds_read_b64_tr_b16 v[120:121], v16 offset:64000
	s_waitcnt lgkmcnt(14)
	v_mfma_f32_32x32x16_bf16 v[66:81], v[162:165], v[102:105], v[66:81]
	v_exp_f32_e32 v158, v158
	v_exp_f32_e32 v159, v159
	ds_read_b64_tr_b16 v[102:103], v16 offset:60416
	ds_read_b64_tr_b16 v[104:105], v16 offset:60928
	s_waitcnt lgkmcnt(14)
	v_mfma_f32_32x32x16_bf16 v[50:65], v[162:165], v[106:109], v[50:65]
	v_exp_f32_e32 v160, v160
	v_exp_f32_e32 v161, v161
	ds_read_b64_tr_b16 v[106:107], v16 offset:64512
	ds_read_b64_tr_b16 v[108:109], v16 offset:65024
	s_waitcnt lgkmcnt(14)
	v_mfma_f32_32x32x16_bf16 v[34:49], v[174:177], v[4:7], v[34:49]
	v_exp_f32_e32 v130, v130
	v_exp_f32_e32 v131, v131
	s_waitcnt lgkmcnt(12)
	v_mfma_f32_32x32x16_bf16 v[18:33], v[174:177], v[8:11], v[18:33]
	v_exp_f32_e32 v132, v132
	v_exp_f32_e32 v133, v133
	v_add_u32_e32 v4, s34, v247
	ds_read_b128 v[98:101], v4
	ds_read_b128 v[194:197], v4 offset:512
	s_waitcnt lgkmcnt(12)
	v_mfma_f32_32x32x16_bf16 v[34:49], v[170:173], v[12:15], v[34:49]
	v_exp_f32_e32 v134, v134
	v_exp_f32_e32 v135, v135
	ds_read_b128 v[190:193], v4 offset:2048
	ds_read_b128 v[186:189], v4 offset:2560
	s_waitcnt lgkmcnt(12)
	v_mfma_f32_32x32x16_bf16 v[18:33], v[170:173], v[110:113], v[18:33]
	v_exp_f32_e32 v136, v136
	v_exp_f32_e32 v137, v137
	ds_read_b128 v[182:185], v4 offset:4096
	ds_read_b128 v[12:15], v4 offset:4608
	s_waitcnt lgkmcnt(12)
	v_mfma_f32_32x32x16_bf16 v[34:49], v[166:169], v[114:117], v[34:49]
	v_exp_f32_e32 v138, v138
	v_exp_f32_e32 v139, v139
	ds_read_b128 v[8:11], v4 offset:6144
	ds_read_b128 v[4:7], v4 offset:6656
	s_waitcnt lgkmcnt(12)
	v_mfma_f32_32x32x16_bf16 v[18:33], v[166:169], v[118:121], v[18:33]
	v_exp_f32_e32 v140, v140
	v_exp_f32_e32 v141, v141
	s_waitcnt lgkmcnt(10)
	v_mfma_f32_32x32x16_bf16 v[34:49], v[162:165], v[102:105], v[34:49]
	v_exp_f32_e32 v142, v142
	v_exp_f32_e32 v143, v143
	s_waitcnt lgkmcnt(8)
	ds_read_b128 v[198:201], v244
	v_mfma_f32_32x32x16_bf16 v[18:33], v[162:165], v[106:109], v[18:33]
	v_exp_f32_e32 v144, v144
	v_exp_f32_e32 v145, v145
	s_waitcnt vmcnt(4) lgkmcnt(0)
	s_barrier
	s_andn2_b64 vcc, exec, s[0:1]
	s_cbranch_vccnz .LBB0_1071
	s_waitcnt lgkmcnt(0)
	v_add_u32_e32 v16, s85, v243
	ds_read_b128 v[102:105], v16 offset:96
	ds_read_b128 v[106:109], v16 offset:64
	ds_read_b128 v[110:113], v16 offset:32
	ds_read_b128 v[114:117], v16
	s_waitcnt lgkmcnt(3)
	v_pk_mul_f32 v[78:79], v[78:79], v[102:103]
	s_waitcnt lgkmcnt(2)
	v_pk_mul_f32 v[74:75], v[74:75], v[106:107]
	s_waitcnt lgkmcnt(1)
	v_pk_mul_f32 v[70:71], v[70:71], v[110:111]
	v_pk_mul_f32 v[80:81], v[80:81], v[104:105]
	v_pk_mul_f32 v[76:77], v[76:77], v[108:109]
	v_pk_mul_f32 v[72:73], v[72:73], v[112:113]
	s_waitcnt lgkmcnt(0)
	v_pk_mul_f32 v[68:69], v[68:69], v[116:117]
	v_pk_mul_f32 v[66:67], v[66:67], v[114:115]
	v_pk_mul_f32 v[62:63], v[62:63], v[102:103]
	v_pk_mul_f32 v[58:59], v[58:59], v[106:107]
	v_pk_mul_f32 v[54:55], v[54:55], v[110:111]
	v_pk_mul_f32 v[64:65], v[64:65], v[104:105]
	v_pk_mul_f32 v[60:61], v[60:61], v[108:109]
	v_pk_mul_f32 v[56:57], v[56:57], v[112:113]
	v_pk_mul_f32 v[52:53], v[52:53], v[116:117]
	v_pk_mul_f32 v[50:51], v[50:51], v[114:115]
	v_pk_mul_f32 v[46:47], v[46:47], v[102:103]
	v_pk_mul_f32 v[42:43], v[42:43], v[106:107]
	v_pk_mul_f32 v[38:39], v[38:39], v[110:111]
	v_pk_mul_f32 v[48:49], v[48:49], v[104:105]
	v_pk_mul_f32 v[44:45], v[44:45], v[108:109]
	v_pk_mul_f32 v[40:41], v[40:41], v[112:113]
	v_pk_mul_f32 v[36:37], v[36:37], v[116:117]
	v_pk_mul_f32 v[34:35], v[34:35], v[114:115]
	v_pk_mul_f32 v[30:31], v[30:31], v[102:103]
	v_pk_mul_f32 v[26:27], v[26:27], v[106:107]
	v_pk_mul_f32 v[22:23], v[22:23], v[110:111]
	v_pk_mul_f32 v[32:33], v[32:33], v[104:105]
	v_pk_mul_f32 v[28:29], v[28:29], v[108:109]
	v_pk_mul_f32 v[24:25], v[24:25], v[112:113]
	v_pk_mul_f32 v[20:21], v[20:21], v[116:117]
	v_pk_mul_f32 v[18:19], v[18:19], v[114:115]
.LBB0_1071:
	s_add_i32 s0, s34, 0x4000
	s_cmpk_lg_u32 s34, 0x8000
	s_cselect_b32 s92, s0, 0
	v_add_u32_e32 v16, s36, v246
	ds_read_b64_tr_b16 v[180:181], v16 offset:49664
	ds_read_b64_tr_b16 v[178:179], v16 offset:49152
	s_waitcnt lgkmcnt(2)
	v_mfma_f32_32x32x16_bf16 v[114:129], v[98:101], v[198:201], v[82:97]
	v_add_f32_e32 v17, v146, v147
	v_add_f32_e32 v17, v148, v17
	v_add_f32_e32 v17, v149, v17
	v_add_f32_e32 v17, v150, v17
	v_add_f32_e32 v17, v151, v17
	v_cvt_pk_bf16_f32 v174, v146, v147
	v_cvt_pk_bf16_f32 v175, v148, v149
	ds_read_b64_tr_b16 v[148:149], v16 offset:53760
	ds_read_b64_tr_b16 v[146:147], v16 offset:53248
	ds_read_b128 v[202:205], v244 offset:1024
	v_mfma_f32_32x32x16_bf16 v[98:113], v[194:197], v[198:201], v[82:97]
	v_add_f32_e32 v17, v152, v17
	v_add_f32_e32 v17, v153, v17
	v_add_f32_e32 v17, v154, v17
	v_add_f32_e32 v17, v155, v17
	v_cvt_pk_bf16_f32 v176, v150, v151
	v_cvt_pk_bf16_f32 v177, v152, v153
	ds_read_b64_tr_b16 v[150:151], v16 offset:50176
	ds_read_b64_tr_b16 v[152:153], v16 offset:50688
	s_waitcnt lgkmcnt(2)
	v_mfma_f32_32x32x16_bf16 v[114:129], v[190:193], v[202:205], v[114:129]
	v_add_f32_e32 v17, v156, v17
	v_add_f32_e32 v17, v157, v17
	v_add_f32_e32 v17, v158, v17
	v_add_f32_e32 v17, v159, v17
	v_cvt_pk_bf16_f32 v170, v154, v155
	v_cvt_pk_bf16_f32 v171, v156, v157
	ds_read_b64_tr_b16 v[156:157], v16 offset:54784
	ds_read_b64_tr_b16 v[154:155], v16 offset:54272
	ds_read_b128 v[190:193], v244 offset:2048
	v_mfma_f32_32x32x16_bf16 v[98:113], v[186:189], v[202:205], v[98:113]
	v_add_f32_e32 v17, v160, v17
	v_add_f32_e32 v17, v161, v17
	v_add_f32_e32 v17, v130, v17
	v_add_f32_e32 v17, v131, v17
	v_cvt_pk_bf16_f32 v172, v158, v159
	v_cvt_pk_bf16_f32 v173, v160, v161
	ds_read_b64_tr_b16 v[158:159], v16 offset:51200
	ds_read_b64_tr_b16 v[160:161], v16 offset:51712
	s_waitcnt lgkmcnt(2)
	v_mfma_f32_32x32x16_bf16 v[114:129], v[182:185], v[190:193], v[114:129]
	v_add_f32_e32 v17, v132, v17
	v_add_f32_e32 v17, v133, v17
	v_add_f32_e32 v17, v134, v17
	v_add_f32_e32 v17, v135, v17
	v_cvt_pk_bf16_f32 v166, v130, v131
	v_cvt_pk_bf16_f32 v167, v132, v133
	ds_read_b64_tr_b16 v[132:133], v16 offset:55808
	ds_read_b64_tr_b16 v[130:131], v16 offset:55296
	ds_read_b128 v[182:185], v244 offset:3072
	v_mfma_f32_32x32x16_bf16 v[98:113], v[12:15], v[190:193], v[98:113]
	v_add_f32_e32 v17, v136, v17
	v_add_f32_e32 v17, v137, v17
	v_add_f32_e32 v17, v138, v17
	v_add_f32_e32 v17, v139, v17
	v_cvt_pk_bf16_f32 v168, v134, v135
	v_cvt_pk_bf16_f32 v169, v136, v137
	ds_read_b64_tr_b16 v[12:13], v16 offset:52224
	ds_read_b64_tr_b16 v[14:15], v16 offset:52736
	s_waitcnt lgkmcnt(2)
	v_mfma_f32_32x32x16_bf16 v[114:129], v[8:11], v[182:185], v[114:129]
	v_add_f32_e32 v17, v140, v17
	v_add_f32_e32 v17, v141, v17
	v_add_f32_e32 v17, v142, v17
	v_add_f32_e32 v17, v143, v17
	v_cvt_pk_bf16_f32 v162, v138, v139
	v_cvt_pk_bf16_f32 v163, v140, v141
	ds_read_b64_tr_b16 v[8:9], v16 offset:56320
	ds_read_b64_tr_b16 v[10:11], v16 offset:56832
	v_mfma_f32_32x32x16_bf16 v[98:113], v[4:7], v[182:185], v[98:113]
	v_add_f32_e32 v17, v144, v17
	v_add_f32_e32 v17, v145, v17
	v_add_f32_e32 v17, 0, v17
	v_cvt_pk_bf16_f32 v164, v142, v143
	v_cvt_pk_bf16_f32 v165, v144, v145
	s_add_i32 s0, s35, -1
	v_max_f32_e32 v4, v115, v115
	v_max_f32_e32 v5, v114, v114
	s_min_i32 s0, s0, s91
	v_max_f32_e32 v4, v5, v4
	s_ashr_i32 s1, s0, 31
	s_nop 0
	v_max3_f32 v5, v116, v117, v99
	v_max3_f32 v4, v4, v98, v100
	s_lshl_b64 s[0:1], s[0:1], 17
	v_max3_f32 v4, v4, v101, v118
	v_max3_f32 v5, v5, v120, v121
	s_add_u32 s0, s87, s0
	v_max3_f32 v4, v4, v119, v102
	v_max3_f32 v5, v5, v104, v105
	s_addc_u32 s1, s88, s1
	s_add_i32 s4, s34, s81
	v_max3_f32 v4, v4, v103, v122
	v_max3_f32 v5, v5, v124, v125
	s_mov_b32 s5, m0
	s_mov_b32 m0, s4
	s_nop 4
	global_load_lds_dwordx4 v237, s[0:1]
	s_mov_b32 m0, s5
	s_add_u32 s0, s0, 0x80
	v_max3_f32 v4, v4, v123, v106
	v_max3_f32 v5, v5, v108, v109
	s_addc_u32 s1, s1, 0
	s_add_i32 s93, s35, -3
	v_max3_f32 v4, v4, v107, v126
	v_max3_f32 v5, v5, v128, v129
	s_add_i32 s4, s34, s82
	s_mov_b32 s5, m0
	s_mov_b32 m0, s4
	s_nop 4
	global_load_lds_dwordx4 v237, s[0:1]
	s_mov_b32 m0, s5
	s_min_i32 s0, s93, s91
	v_max3_f32 v4, v4, v127, v110
	v_max3_f32 v5, v5, v112, v113
	s_ashr_i32 s1, s0, 31
	v_add_f32_e32 v248, v2, v17
	v_max3_f32 v2, v4, v111, v5
	s_lshl_b64 s[0:1], s[0:1], 17
	v_mov_b32_e32 v4, v2
	s_add_u32 s0, s89, s0
	s_nop 0
	v_permlane32_swap_b32_e32 v2, v4
	s_addc_u32 s1, s90, s1
	s_add_i32 s4, s92, s80
	v_max_f32_e32 v4, v4, v4
	v_max_f32_e32 v2, v2, v2
	s_mov_b32 s5, m0
	s_mov_b32 m0, s4
	s_nop 4
	global_load_lds_dwordx4 v238, s[0:1]
	s_mov_b32 m0, s5
	s_add_u32 s0, s0, 0x80
	v_max_f32_e32 v2, v2, v4
	s_addc_u32 s1, s1, 0
	s_add_i32 s4, s92, s84
	s_mov_b32 s5, m0
	s_mov_b32 m0, s4
	s_nop 4
	global_load_lds_dwordx4 v238, s[0:1]
	s_mov_b32 m0, s5
	v_cmp_lt_f32_e32 vcc, s62, v2
	s_cmp_lg_u64 vcc, 0
	s_cselect_b64 s[0:1], -1, 0
	s_cbranch_vccnz .LBB0_1079
.LBB0_1072:
	v_mfma_f32_32x32x16_bf16 v[66:81], v[174:177], v[178:181], v[66:81]
	v_exp_f32_e32 v114, v114
	v_exp_f32_e32 v115, v115
	ds_read_b64_tr_b16 v[4:5], v16 offset:57344
	ds_read_b64_tr_b16 v[6:7], v16 offset:57856
	v_mfma_f32_32x32x16_bf16 v[50:65], v[174:177], v[146:149], v[50:65]
	v_exp_f32_e32 v116, v116
	v_exp_f32_e32 v117, v117
	ds_read_b64_tr_b16 v[134:135], v16 offset:61440
	ds_read_b64_tr_b16 v[136:137], v16 offset:61952
	v_mfma_f32_32x32x16_bf16 v[66:81], v[170:173], v[150:153], v[66:81]
	v_exp_f32_e32 v118, v118
	v_exp_f32_e32 v119, v119
	ds_read_b64_tr_b16 v[138:139], v16 offset:58368
	ds_read_b64_tr_b16 v[140:141], v16 offset:58880
	v_mfma_f32_32x32x16_bf16 v[50:65], v[170:173], v[154:157], v[50:65]
	v_exp_f32_e32 v120, v120
	v_exp_f32_e32 v121, v121
	ds_read_b64_tr_b16 v[142:143], v16 offset:62464
	ds_read_b64_tr_b16 v[144:145], v16 offset:62976
	v_mfma_f32_32x32x16_bf16 v[66:81], v[166:169], v[158:161], v[66:81]
	v_exp_f32_e32 v122, v122
	v_exp_f32_e32 v123, v123
	ds_read_b64_tr_b16 v[146:147], v16 offset:59392
	ds_read_b64_tr_b16 v[148:149], v16 offset:59904
	v_mfma_f32_32x32x16_bf16 v[50:65], v[166:169], v[130:133], v[50:65]
	v_exp_f32_e32 v124, v124
	v_exp_f32_e32 v125, v125
	ds_read_b64_tr_b16 v[130:131], v16 offset:63488
	ds_read_b64_tr_b16 v[132:133], v16 offset:64000
	s_waitcnt lgkmcnt(14)
	v_mfma_f32_32x32x16_bf16 v[66:81], v[162:165], v[12:15], v[66:81]
	v_exp_f32_e32 v126, v126
	v_exp_f32_e32 v127, v127
	ds_read_b64_tr_b16 v[12:13], v16 offset:60416
	ds_read_b64_tr_b16 v[14:15], v16 offset:60928
	s_waitcnt lgkmcnt(14)
	v_mfma_f32_32x32x16_bf16 v[50:65], v[162:165], v[8:11], v[50:65]
	v_exp_f32_e32 v128, v128
	v_exp_f32_e32 v129, v129
	ds_read_b64_tr_b16 v[8:9], v16 offset:64512
	ds_read_b64_tr_b16 v[10:11], v16 offset:65024
	s_waitcnt lgkmcnt(14)
	v_mfma_f32_32x32x16_bf16 v[34:49], v[174:177], v[4:7], v[34:49]
	v_exp_f32_e32 v98, v98
	v_exp_f32_e32 v99, v99
	s_waitcnt lgkmcnt(12)
	v_mfma_f32_32x32x16_bf16 v[18:33], v[174:177], v[134:137], v[18:33]
	v_exp_f32_e32 v100, v100
	v_exp_f32_e32 v101, v101
	v_add_u32_e32 v2, s92, v247
	ds_read_b128 v[206:209], v2
	ds_read_b128 v[202:205], v2 offset:512
	s_waitcnt lgkmcnt(12)
	v_mfma_f32_32x32x16_bf16 v[34:49], v[170:173], v[138:141], v[34:49]
	v_exp_f32_e32 v102, v102
	v_exp_f32_e32 v103, v103
	ds_read_b128 v[198:201], v2 offset:2048
	ds_read_b128 v[194:197], v2 offset:2560
	s_waitcnt lgkmcnt(12)
	v_mfma_f32_32x32x16_bf16 v[18:33], v[170:173], v[142:145], v[18:33]
	v_exp_f32_e32 v104, v104
	v_exp_f32_e32 v105, v105
	ds_read_b128 v[190:193], v2 offset:4096
	ds_read_b128 v[186:189], v2 offset:4608
	s_waitcnt lgkmcnt(12)
	v_mfma_f32_32x32x16_bf16 v[34:49], v[166:169], v[146:149], v[34:49]
	v_exp_f32_e32 v106, v106
	v_exp_f32_e32 v107, v107
	ds_read_b128 v[182:185], v2 offset:6144
	ds_read_b128 v[178:181], v2 offset:6656
	s_waitcnt lgkmcnt(12)
	v_mfma_f32_32x32x16_bf16 v[18:33], v[166:169], v[130:133], v[18:33]
	v_exp_f32_e32 v108, v108
	v_exp_f32_e32 v109, v109
	s_waitcnt lgkmcnt(10)
	v_mfma_f32_32x32x16_bf16 v[34:49], v[162:165], v[12:15], v[34:49]
	v_exp_f32_e32 v110, v110
	v_exp_f32_e32 v111, v111
	s_waitcnt lgkmcnt(8)
	ds_read_b128 v[210:213], v244
	v_mfma_f32_32x32x16_bf16 v[18:33], v[162:165], v[8:11], v[18:33]
	v_exp_f32_e32 v112, v112
	v_exp_f32_e32 v113, v113
	s_waitcnt vmcnt(4) lgkmcnt(0)
	s_barrier
	s_andn2_b64 vcc, exec, s[0:1]
	s_cbranch_vccnz .LBB0_1074
	s_waitcnt lgkmcnt(0)
	v_add_u32_e32 v2, s85, v243
	ds_read_b128 v[4:7], v2 offset:96
	ds_read_b128 v[8:11], v2 offset:64
	ds_read_b128 v[12:15], v2 offset:32
	ds_read_b128 v[130:133], v2
	s_waitcnt lgkmcnt(3)
	v_pk_mul_f32 v[78:79], v[78:79], v[4:5]
	s_waitcnt lgkmcnt(2)
	v_pk_mul_f32 v[74:75], v[74:75], v[8:9]
	s_waitcnt lgkmcnt(1)
	v_pk_mul_f32 v[70:71], v[70:71], v[12:13]
	v_pk_mul_f32 v[80:81], v[80:81], v[6:7]
	v_pk_mul_f32 v[76:77], v[76:77], v[10:11]
	v_pk_mul_f32 v[72:73], v[72:73], v[14:15]
	s_waitcnt lgkmcnt(0)
	v_pk_mul_f32 v[68:69], v[68:69], v[132:133]
	v_pk_mul_f32 v[66:67], v[66:67], v[130:131]
	v_pk_mul_f32 v[62:63], v[62:63], v[4:5]
	v_pk_mul_f32 v[58:59], v[58:59], v[8:9]
	v_pk_mul_f32 v[54:55], v[54:55], v[12:13]
	v_pk_mul_f32 v[64:65], v[64:65], v[6:7]
	v_pk_mul_f32 v[60:61], v[60:61], v[10:11]
	v_pk_mul_f32 v[56:57], v[56:57], v[14:15]
	v_pk_mul_f32 v[52:53], v[52:53], v[132:133]
	v_pk_mul_f32 v[50:51], v[50:51], v[130:131]
	v_pk_mul_f32 v[46:47], v[46:47], v[4:5]
	v_pk_mul_f32 v[42:43], v[42:43], v[8:9]
	v_pk_mul_f32 v[38:39], v[38:39], v[12:13]
	v_pk_mul_f32 v[48:49], v[48:49], v[6:7]
	v_pk_mul_f32 v[44:45], v[44:45], v[10:11]
	v_pk_mul_f32 v[40:41], v[40:41], v[14:15]
	v_pk_mul_f32 v[36:37], v[36:37], v[132:133]
	v_pk_mul_f32 v[34:35], v[34:35], v[130:131]
	v_pk_mul_f32 v[30:31], v[30:31], v[4:5]
	v_pk_mul_f32 v[26:27], v[26:27], v[8:9]
	v_pk_mul_f32 v[22:23], v[22:23], v[12:13]
	v_pk_mul_f32 v[32:33], v[32:33], v[6:7]
	v_pk_mul_f32 v[28:29], v[28:29], v[10:11]
	v_pk_mul_f32 v[24:25], v[24:25], v[14:15]
	v_pk_mul_f32 v[20:21], v[20:21], v[132:133]
	v_pk_mul_f32 v[18:19], v[18:19], v[130:131]
